# neighbourhood attention bias loads: per-element index math (sub, clamp, shift-add) folded into one per-lane base plus immediate offsets
# speedup vs baseline: 1.0207x; 1.0015x over previous
;     ...
;             const bool biased = BIAS && t < nlat;
;             if (biased) {
;                 const int drow = (kr0 + t - qr + 7) * 32;
;                 int qcl = qc, csl = cs; asm volatile("" : "+v"(qcl), "+v"(csl));
.LBB0_476:
	s_andn2_b64 vcc, exec, s[2:3]
	s_mov_b64 s[48:49], 0
	s_cbranch_vccnz .LBB0_510
	v_mov_b32_e32 v114, v192
	v_mov_b32_e32 v176, v193
	s_add_i32 s4, s70, s71

; __device__ __forceinline__ int crow(int r, int h) { return (r & 3) + 8 * (r >> 2) + 4 * h; }
;     ...
;                     const int k0 = crow(r, h2), k1 = k0 + 32;
;                     int d0 = k0 - qcl + 15, d1 = k1 - qcl + 15; d0 = d0 < 0 ? 0 : (d0 > 30 ? 30 : d0); d1 = d1 < 0 ? 0 : (d1 > 30 ? 30 : d1);
;                     const float b0 = rpbL[drow + d0], b1 = rpbL[drow + d1];
	v_sub_u32_e32 v166, v188, v114
	v_lshl_add_u32 v166, v166, 2, s4
	v_add_u32_e32 v166, 0xafbc, v166

; __device__ __forceinline__ int crow(int r, int h) { return (r & 3) + 8 * (r >> 2) + 4 * h; }
;     ...
;                     const int k0 = crow(r, h2), k1 = k0 + 32;
;                     int d0 = k0 - qcl + 15, d1 = k1 - qcl + 15; d0 = d0 < 0 ? 0 : (d0 > 30 ? 30 : d0); d1 = d1 < 0 ? 0 : (d1 > 30 ? 30 : d1);
;                     const float b0 = rpbL[drow + d0], b1 = rpbL[drow + d1];
;                     s0[r] = ((unsigned)(k0 - csl) < 16u) ? s0[r] * C2S + b0 * LOG2E : -1e30f;
;                     s1[r] = ((unsigned)(k1 - csl) < 16u) ? s1[r] * C2S + b1 * LOG2E : -1e30f;
	ds_read_b32 v106, v166
	ds_read_b32 v107, v166 offset:4
	ds_read_b32 v108, v166 offset:8
	ds_read_b32 v109, v166 offset:12
	ds_read_b32 v110, v166 offset:32
	ds_read_b32 v111, v166 offset:36
	ds_read_b32 v112, v166 offset:40
	ds_read_b32 v113, v166 offset:44
	ds_read_b32 v116, v166 offset:64
	ds_read_b32 v118, v166 offset:68
	ds_read_b32 v120, v166 offset:72
	ds_read_b32 v122, v166 offset:76
	ds_read_b32 v124, v166 offset:96
	ds_read_b32 v126, v166 offset:100
	ds_read_b32 v128, v166 offset:104
	ds_read_b32 v164, v166 offset:108
	s_waitcnt lgkmcnt(0)
	v_sub_u32_e32 v168, v188, v176
	v_cmp_gt_u32_e32 vcc, 16, v168
	v_mul_f32_e32 v98, s20, v48
	v_mul_f32_e32 v106, s21, v106
	v_add_f32_e32 v98, v98, v106
	v_cndmask_b32_e32 v98, v202, v98, vcc

;     ...
;                     s0[r] = ((unsigned)(k0 - csl) < 16u) ? s0[r] * C2S + b0 * LOG2E : -1e30f;
	v_sub_u32_e32 v168, v212, v176
	v_cmp_gt_u32_e32 vcc, 16, v168
	v_mul_f32_e32 v99, s20, v49
	v_mul_f32_e32 v107, s21, v107
	v_add_f32_e32 v99, v99, v107
	v_cndmask_b32_e32 v99, v202, v99, vcc

;     ...
;                     s0[r] = ((unsigned)(k0 - csl) < 16u) ? s0[r] * C2S + b0 * LOG2E : -1e30f;
	v_sub_u32_e32 v168, v214, v176
	v_cmp_gt_u32_e32 vcc, 16, v168
	v_mul_f32_e32 v100, s20, v50
	v_mul_f32_e32 v108, s21, v108
	v_add_f32_e32 v100, v100, v108
	v_cndmask_b32_e32 v100, v202, v100, vcc

;     ...
;                     s0[r] = ((unsigned)(k0 - csl) < 16u) ? s0[r] * C2S + b0 * LOG2E : -1e30f;
	v_sub_u32_e32 v168, v216, v176
	v_cmp_gt_u32_e32 vcc, 16, v168
	v_mul_f32_e32 v101, s20, v51
	v_mul_f32_e32 v109, s21, v109
	v_add_f32_e32 v101, v101, v109
	v_cndmask_b32_e32 v101, v202, v101, vcc

;     ...
;                     s0[r] = ((unsigned)(k0 - csl) < 16u) ? s0[r] * C2S + b0 * LOG2E : -1e30f;
	v_sub_u32_e32 v168, v218, v176
	v_cmp_gt_u32_e32 vcc, 16, v168
	v_mul_f32_e32 v102, s20, v52
	v_mul_f32_e32 v110, s21, v110
	v_add_f32_e32 v102, v102, v110
	v_cndmask_b32_e32 v102, v202, v102, vcc

;     ...
;                     s0[r] = ((unsigned)(k0 - csl) < 16u) ? s0[r] * C2S + b0 * LOG2E : -1e30f;
	v_sub_u32_e32 v168, v220, v176
	v_cmp_gt_u32_e32 vcc, 16, v168
	v_mul_f32_e32 v103, s20, v53
	v_mul_f32_e32 v111, s21, v111
	v_add_f32_e32 v103, v103, v111
	v_cndmask_b32_e32 v103, v202, v103, vcc

;     ...
;                     s0[r] = ((unsigned)(k0 - csl) < 16u) ? s0[r] * C2S + b0 * LOG2E : -1e30f;
	v_sub_u32_e32 v168, v222, v176
	v_cmp_gt_u32_e32 vcc, 16, v168
	v_mul_f32_e32 v104, s20, v54
	v_mul_f32_e32 v112, s21, v112
	v_add_f32_e32 v104, v104, v112
	v_cndmask_b32_e32 v104, v202, v104, vcc

;     ...
;                     s0[r] = ((unsigned)(k0 - csl) < 16u) ? s0[r] * C2S + b0 * LOG2E : -1e30f;
	v_sub_u32_e32 v168, v224, v176
	v_cmp_gt_u32_e32 vcc, 16, v168
	v_mul_f32_e32 v105, s20, v55
	v_mul_f32_e32 v113, s21, v113
	v_add_f32_e32 v105, v105, v113
	v_cndmask_b32_e32 v105, v202, v105, vcc

;     ...
;                     s0[r] = ((unsigned)(k0 - csl) < 16u) ? s0[r] * C2S + b0 * LOG2E : -1e30f;
	v_sub_u32_e32 v168, v226, v176
	v_cmp_gt_u32_e32 vcc, 16, v168
	v_mul_f32_e32 v106, s20, v56
	v_mul_f32_e32 v116, s21, v116
	v_add_f32_e32 v106, v106, v116
	v_cndmask_b32_e32 v106, v202, v106, vcc

;     ...
;                     s0[r] = ((unsigned)(k0 - csl) < 16u) ? s0[r] * C2S + b0 * LOG2E : -1e30f;
	v_sub_u32_e32 v168, v228, v176
	v_cmp_gt_u32_e32 vcc, 16, v168
	v_mul_f32_e32 v107, s20, v57
	v_mul_f32_e32 v118, s21, v118
	v_add_f32_e32 v107, v107, v118
	v_cndmask_b32_e32 v107, v202, v107, vcc

;     ...
;                     s0[r] = ((unsigned)(k0 - csl) < 16u) ? s0[r] * C2S + b0 * LOG2E : -1e30f;
	v_sub_u32_e32 v168, v230, v176
	v_cmp_gt_u32_e32 vcc, 16, v168
	v_mul_f32_e32 v108, s20, v58
	v_mul_f32_e32 v120, s21, v120
	v_add_f32_e32 v108, v108, v120
	v_cndmask_b32_e32 v108, v202, v108, vcc

;     ...
;                     s0[r] = ((unsigned)(k0 - csl) < 16u) ? s0[r] * C2S + b0 * LOG2E : -1e30f;
	v_sub_u32_e32 v168, v232, v176
	v_cmp_gt_u32_e32 vcc, 16, v168
	v_mul_f32_e32 v109, s20, v59
	v_mul_f32_e32 v122, s21, v122
	v_add_f32_e32 v109, v109, v122
	v_cndmask_b32_e32 v109, v202, v109, vcc

;     ...
;                     s0[r] = ((unsigned)(k0 - csl) < 16u) ? s0[r] * C2S + b0 * LOG2E : -1e30f;
	v_sub_u32_e32 v168, v234, v176
	v_cmp_gt_u32_e32 vcc, 16, v168
	v_mul_f32_e32 v110, s20, v60
	v_mul_f32_e32 v124, s21, v124
	v_add_f32_e32 v110, v110, v124
	v_cndmask_b32_e32 v110, v202, v110, vcc

;     ...
;                     s0[r] = ((unsigned)(k0 - csl) < 16u) ? s0[r] * C2S + b0 * LOG2E : -1e30f;
	v_sub_u32_e32 v168, v236, v176
	v_cmp_gt_u32_e32 vcc, 16, v168
	v_mul_f32_e32 v111, s20, v61
	v_mul_f32_e32 v126, s21, v126
	v_add_f32_e32 v111, v111, v126
	v_cndmask_b32_e32 v111, v202, v111, vcc

;     ...
;                     s0[r] = ((unsigned)(k0 - csl) < 16u) ? s0[r] * C2S + b0 * LOG2E : -1e30f;
	v_sub_u32_e32 v168, v238, v176
	v_cmp_gt_u32_e32 vcc, 16, v168
	v_mul_f32_e32 v112, s20, v62
	v_mul_f32_e32 v128, s21, v128
	v_add_f32_e32 v112, v112, v128
	v_cndmask_b32_e32 v112, v202, v112, vcc

;     ...
;                     s0[r] = ((unsigned)(k0 - csl) < 16u) ? s0[r] * C2S + b0 * LOG2E : -1e30f;
	v_sub_u32_e32 v168, v240, v176
	v_cmp_gt_u32_e32 vcc, 16, v168
	v_mul_f32_e32 v113, s20, v63
	v_mul_f32_e32 v164, s21, v164
	v_add_f32_e32 v113, v113, v164
	v_cndmask_b32_e32 v113, v202, v113, vcc

; __device__ __forceinline__ int crow(int r, int h) { return (r & 3) + 8 * (r >> 2) + 4 * h; }
;     ...
;                     const int k0 = crow(r, h2), k1 = k0 + 32;
;                     int d0 = k0 - qcl + 15, d1 = k1 - qcl + 15; d0 = d0 < 0 ? 0 : (d0 > 30 ? 30 : d0); d1 = d1 < 0 ? 0 : (d1 > 30 ? 30 : d1);
;                     const float b0 = rpbL[drow + d0], b1 = rpbL[drow + d1];
;                     s0[r] = ((unsigned)(k0 - csl) < 16u) ? s0[r] * C2S + b0 * LOG2E : -1e30f;
;                     s1[r] = ((unsigned)(k1 - csl) < 16u) ? s1[r] * C2S + b1 * LOG2E : -1e30f;
;                 }
	ds_read_b32 v115, v166 offset:128
	ds_read_b32 v117, v166 offset:132
	ds_read_b32 v119, v166 offset:136
	ds_read_b32 v121, v166 offset:140
	ds_read_b32 v123, v166 offset:160
	ds_read_b32 v125, v166 offset:164
	ds_read_b32 v127, v166 offset:168
	ds_read_b32 v129, v166 offset:172
	ds_read_b32 v165, v166 offset:192
	ds_read_b32 v167, v166 offset:196
	ds_read_b32 v169, v166 offset:200
	ds_read_b32 v171, v166 offset:204
	ds_read_b32 v173, v166 offset:224
	ds_read_b32 v175, v166 offset:228
	ds_read_b32 v179, v166 offset:232
	ds_read_b32 v177, v166 offset:236
	v_sub_u32_e32 v114, v211, v176
	v_cmp_gt_u32_e32 vcc, 16, v114
	v_mov_b32_e32 v114, v32
	s_waitcnt lgkmcnt(14)
	v_pk_mul_f32 v[114:115], v[114:115], s[20:21]
	v_mov_b32_e32 v116, v33
	v_add_f32_e32 v114, v114, v115
	v_sub_u32_e32 v115, v213, v176
	v_pk_mul_f32 v[116:117], v[116:117], s[20:21]
	v_cndmask_b32_e32 v114, v202, v114, vcc
	v_cmp_gt_u32_e32 vcc, 16, v115
	v_add_f32_e32 v115, v116, v117
	v_sub_u32_e32 v116, v215, v176
	v_mov_b32_e32 v118, v34
	v_cndmask_b32_e32 v115, v202, v115, vcc
	v_cmp_gt_u32_e32 vcc, 16, v116
	s_waitcnt lgkmcnt(13)
	v_pk_mul_f32 v[116:117], v[118:119], s[20:21]
	v_mov_b32_e32 v120, v35
	v_add_f32_e32 v116, v116, v117
	v_sub_u32_e32 v117, v217, v176
	s_waitcnt lgkmcnt(12)
	v_pk_mul_f32 v[118:119], v[120:121], s[20:21]
	v_cndmask_b32_e32 v116, v202, v116, vcc
	v_cmp_gt_u32_e32 vcc, 16, v117
	v_add_f32_e32 v117, v118, v119
	v_sub_u32_e32 v118, v219, v176
	v_mov_b32_e32 v122, v36
	v_cndmask_b32_e32 v117, v202, v117, vcc
	v_cmp_gt_u32_e32 vcc, 16, v118
	s_waitcnt lgkmcnt(11)
	v_pk_mul_f32 v[118:119], v[122:123], s[20:21]
	v_mov_b32_e32 v124, v37
	v_add_f32_e32 v118, v118, v119
	v_sub_u32_e32 v119, v221, v176
	s_waitcnt lgkmcnt(10)
	v_pk_mul_f32 v[120:121], v[124:125], s[20:21]
	v_cndmask_b32_e32 v118, v202, v118, vcc
	v_cmp_gt_u32_e32 vcc, 16, v119
	v_add_f32_e32 v119, v120, v121
	v_sub_u32_e32 v120, v223, v176
	v_mov_b32_e32 v126, v38
	v_cndmask_b32_e32 v119, v202, v119, vcc
	v_cmp_gt_u32_e32 vcc, 16, v120
	s_waitcnt lgkmcnt(9)
	v_pk_mul_f32 v[120:121], v[126:127], s[20:21]
	v_mov_b32_e32 v128, v39
	v_add_f32_e32 v120, v120, v121
	v_sub_u32_e32 v121, v225, v176
	s_waitcnt lgkmcnt(8)
	v_pk_mul_f32 v[122:123], v[128:129], s[20:21]
	v_cndmask_b32_e32 v120, v202, v120, vcc
	v_cmp_gt_u32_e32 vcc, 16, v121
	v_add_f32_e32 v121, v122, v123
	v_sub_u32_e32 v122, v227, v176
	v_mov_b32_e32 v164, v40
	v_cndmask_b32_e32 v121, v202, v121, vcc
	v_cmp_gt_u32_e32 vcc, 16, v122
	s_waitcnt lgkmcnt(7)
	v_pk_mul_f32 v[122:123], v[164:165], s[20:21]
	v_mov_b32_e32 v166, v41
	v_add_f32_e32 v122, v122, v123
	v_sub_u32_e32 v123, v229, v176
	s_waitcnt lgkmcnt(6)
	v_pk_mul_f32 v[124:125], v[166:167], s[20:21]
	v_cndmask_b32_e32 v122, v202, v122, vcc
	v_cmp_gt_u32_e32 vcc, 16, v123
	v_add_f32_e32 v123, v124, v125
	v_sub_u32_e32 v124, v231, v176
	v_mov_b32_e32 v168, v42
	v_cndmask_b32_e32 v123, v202, v123, vcc
	v_cmp_gt_u32_e32 vcc, 16, v124
	s_waitcnt lgkmcnt(5)
	v_pk_mul_f32 v[124:125], v[168:169], s[20:21]
	v_mov_b32_e32 v170, v43
	v_add_f32_e32 v124, v124, v125
	v_sub_u32_e32 v125, v233, v176
	s_waitcnt lgkmcnt(4)
	v_pk_mul_f32 v[126:127], v[170:171], s[20:21]
	v_cndmask_b32_e32 v124, v202, v124, vcc
	v_cmp_gt_u32_e32 vcc, 16, v125
	v_add_f32_e32 v125, v126, v127
	v_sub_u32_e32 v126, v235, v176
	v_mov_b32_e32 v172, v44
	v_cndmask_b32_e32 v125, v202, v125, vcc
	v_cmp_gt_u32_e32 vcc, 16, v126
	s_waitcnt lgkmcnt(3)
	v_pk_mul_f32 v[126:127], v[172:173], s[20:21]
	v_mov_b32_e32 v174, v45
	v_add_f32_e32 v126, v126, v127
	v_sub_u32_e32 v127, v237, v176
	s_waitcnt lgkmcnt(2)
	v_pk_mul_f32 v[128:129], v[174:175], s[20:21]
	v_cndmask_b32_e32 v126, v202, v126, vcc
	v_cmp_gt_u32_e32 vcc, 16, v127
	v_add_f32_e32 v127, v128, v129
	v_sub_u32_e32 v128, v239, v176
	v_mov_b32_e32 v178, v46
	v_cndmask_b32_e32 v127, v202, v127, vcc
	v_cmp_gt_u32_e32 vcc, 16, v128
	s_waitcnt lgkmcnt(1)
	v_pk_mul_f32 v[128:129], v[178:179], s[20:21]
	s_mov_b64 s[48:49], -1
	v_add_f32_e32 v128, v128, v129
	v_sub_u32_e32 v129, v241, v176
	v_mov_b32_e32 v176, v47
	s_waitcnt lgkmcnt(0)
	v_pk_mul_f32 v[164:165], v[176:177], s[20:21]
	v_cndmask_b32_e32 v128, v202, v128, vcc
	v_cmp_gt_u32_e32 vcc, 16, v129
	v_add_f32_e32 v129, v164, v165
	s_nop 0
	v_cndmask_b32_e32 v129, v202, v129, vcc

;     ...
;         if (tile_act(t)) {
;             float mx;
;             const bool biased = BIAS && t < nlat;
;             if (biased) {
;                 const int drow = (kr0 + t - qr + 7) * 32;
;                 int qcl = qc, csl = cs; asm volatile("" : "+v"(qcl), "+v"(csl));
.LBB0_532:
	v_readlane_b32 s78, v255, 2
	s_andn2_b64 vcc, exec, s[2:3]
	s_mov_b64 s[48:49], 0
	v_readlane_b32 s79, v255, 3
	s_cbranch_vccnz .LBB0_566
	v_mov_b32_e32 v114, v192
	v_mov_b32_e32 v167, v193
	s_add_i32 s4, s70, s71

; __device__ __forceinline__ int crow(int r, int h) { return (r & 3) + 8 * (r >> 2) + 4 * h; }
;     ...
;                     const int k0 = crow(r, h2), k1 = k0 + 32;
;                     int d0 = k0 - qcl + 15, d1 = k1 - qcl + 15; d0 = d0 < 0 ? 0 : (d0 > 30 ? 30 : d0); d1 = d1 < 0 ? 0 : (d1 > 30 ? 30 : d1);
;                     const float b0 = rpbL[drow + d0], b1 = rpbL[drow + d1];
	v_sub_u32_e32 v168, v188, v114
	v_lshl_add_u32 v168, v168, 2, s4
	v_add_u32_e32 v168, 0xb03c, v168

; __device__ __forceinline__ int crow(int r, int h) { return (r & 3) + 8 * (r >> 2) + 4 * h; }
;     ...
;                     const int k0 = crow(r, h2), k1 = k0 + 32;
;                     int d0 = k0 - qcl + 15, d1 = k1 - qcl + 15; d0 = d0 < 0 ? 0 : (d0 > 30 ? 30 : d0); d1 = d1 < 0 ? 0 : (d1 > 30 ? 30 : d1);
;                     const float b0 = rpbL[drow + d0], b1 = rpbL[drow + d1];
;                     s0[r] = ((unsigned)(k0 - csl) < 16u) ? s0[r] * C2S + b0 * LOG2E : -1e30f;
	ds_read_b32 v98, v168
	ds_read_b32 v99, v168 offset:4
	ds_read_b32 v100, v168 offset:8
	ds_read_b32 v101, v168 offset:12
	ds_read_b32 v102, v168 offset:32
	ds_read_b32 v103, v168 offset:36
	ds_read_b32 v104, v168 offset:40
	ds_read_b32 v105, v168 offset:44
	ds_read_b32 v106, v168 offset:64
	ds_read_b32 v107, v168 offset:68
	ds_read_b32 v108, v168 offset:72
	ds_read_b32 v109, v168 offset:76
	ds_read_b32 v110, v168 offset:96
	ds_read_b32 v111, v168 offset:100
	ds_read_b32 v112, v168 offset:104
	ds_read_b32 v113, v168 offset:108
	s_waitcnt lgkmcnt(0)
	v_sub_u32_e32 v169, v188, v167
	v_cmp_gt_u32_e32 vcc, 16, v169
	v_mul_f32_e32 v98, s21, v98
	v_mul_f32_e32 v168, s20, v82
	v_add_f32_e32 v98, v168, v98
	v_cndmask_b32_e32 v98, v202, v98, vcc

;     ...
;                     s0[r] = ((unsigned)(k0 - csl) < 16u) ? s0[r] * C2S + b0 * LOG2E : -1e30f;
	v_sub_u32_e32 v169, v212, v167
	v_cmp_gt_u32_e32 vcc, 16, v169
	v_mul_f32_e32 v99, s21, v99
	v_mul_f32_e32 v168, s20, v83
	v_add_f32_e32 v99, v168, v99
	v_cndmask_b32_e32 v99, v202, v99, vcc

;     ...
;                     s0[r] = ((unsigned)(k0 - csl) < 16u) ? s0[r] * C2S + b0 * LOG2E : -1e30f;
	v_sub_u32_e32 v169, v214, v167
	v_cmp_gt_u32_e32 vcc, 16, v169
	v_mul_f32_e32 v100, s21, v100
	v_mul_f32_e32 v168, s20, v84
	v_add_f32_e32 v100, v168, v100
	v_cndmask_b32_e32 v100, v202, v100, vcc

;     ...
;                     s0[r] = ((unsigned)(k0 - csl) < 16u) ? s0[r] * C2S + b0 * LOG2E : -1e30f;
	v_sub_u32_e32 v169, v216, v167
	v_cmp_gt_u32_e32 vcc, 16, v169
	v_mul_f32_e32 v101, s21, v101
	v_mul_f32_e32 v168, s20, v85
	v_add_f32_e32 v101, v168, v101
	v_cndmask_b32_e32 v101, v202, v101, vcc

;     ...
;                     s0[r] = ((unsigned)(k0 - csl) < 16u) ? s0[r] * C2S + b0 * LOG2E : -1e30f;
	v_sub_u32_e32 v169, v218, v167
	v_cmp_gt_u32_e32 vcc, 16, v169
	v_mul_f32_e32 v102, s21, v102
	v_mul_f32_e32 v168, s20, v86
	v_add_f32_e32 v102, v168, v102
	v_cndmask_b32_e32 v102, v202, v102, vcc

;     ...
;                     s0[r] = ((unsigned)(k0 - csl) < 16u) ? s0[r] * C2S + b0 * LOG2E : -1e30f;
	v_sub_u32_e32 v169, v220, v167
	v_cmp_gt_u32_e32 vcc, 16, v169
	v_mul_f32_e32 v103, s21, v103
	v_mul_f32_e32 v168, s20, v87
	v_add_f32_e32 v103, v168, v103
	v_cndmask_b32_e32 v103, v202, v103, vcc

;     ...
;                     s0[r] = ((unsigned)(k0 - csl) < 16u) ? s0[r] * C2S + b0 * LOG2E : -1e30f;
	v_sub_u32_e32 v169, v222, v167
	v_cmp_gt_u32_e32 vcc, 16, v169
	v_mul_f32_e32 v104, s21, v104
	v_mul_f32_e32 v168, s20, v88
	v_add_f32_e32 v104, v168, v104
	v_cndmask_b32_e32 v104, v202, v104, vcc

;     ...
;                     s0[r] = ((unsigned)(k0 - csl) < 16u) ? s0[r] * C2S + b0 * LOG2E : -1e30f;
	v_sub_u32_e32 v169, v224, v167
	v_cmp_gt_u32_e32 vcc, 16, v169
	v_mul_f32_e32 v105, s21, v105
	v_mul_f32_e32 v168, s20, v89
	v_add_f32_e32 v105, v168, v105
	v_cndmask_b32_e32 v105, v202, v105, vcc

;     ...
;                     s0[r] = ((unsigned)(k0 - csl) < 16u) ? s0[r] * C2S + b0 * LOG2E : -1e30f;
	v_sub_u32_e32 v169, v226, v167
	v_cmp_gt_u32_e32 vcc, 16, v169
	v_mul_f32_e32 v106, s21, v106
	v_mul_f32_e32 v168, s20, v90
	v_add_f32_e32 v106, v168, v106
	v_cndmask_b32_e32 v106, v202, v106, vcc

;     ...
;                     s0[r] = ((unsigned)(k0 - csl) < 16u) ? s0[r] * C2S + b0 * LOG2E : -1e30f;
	v_sub_u32_e32 v169, v228, v167
	v_cmp_gt_u32_e32 vcc, 16, v169
	v_mul_f32_e32 v107, s21, v107
	v_mul_f32_e32 v168, s20, v91
	v_add_f32_e32 v107, v168, v107
	v_cndmask_b32_e32 v107, v202, v107, vcc

;     ...
;                     s0[r] = ((unsigned)(k0 - csl) < 16u) ? s0[r] * C2S + b0 * LOG2E : -1e30f;
	v_sub_u32_e32 v169, v230, v167
	v_cmp_gt_u32_e32 vcc, 16, v169
	v_mul_f32_e32 v108, s21, v108
	v_mul_f32_e32 v168, s20, v92
	v_add_f32_e32 v108, v168, v108
	v_cndmask_b32_e32 v108, v202, v108, vcc

;     ...
;                     s0[r] = ((unsigned)(k0 - csl) < 16u) ? s0[r] * C2S + b0 * LOG2E : -1e30f;
	v_sub_u32_e32 v169, v232, v167
	v_cmp_gt_u32_e32 vcc, 16, v169
	v_mul_f32_e32 v109, s21, v109
	v_mul_f32_e32 v168, s20, v93
	v_add_f32_e32 v109, v168, v109
	v_cndmask_b32_e32 v109, v202, v109, vcc

;     ...
;                     s0[r] = ((unsigned)(k0 - csl) < 16u) ? s0[r] * C2S + b0 * LOG2E : -1e30f;
	v_sub_u32_e32 v169, v234, v167
	v_cmp_gt_u32_e32 vcc, 16, v169
	v_mul_f32_e32 v110, s21, v110
	v_mul_f32_e32 v168, s20, v94
	v_add_f32_e32 v110, v168, v110
	v_cndmask_b32_e32 v110, v202, v110, vcc

;     ...
;                     s0[r] = ((unsigned)(k0 - csl) < 16u) ? s0[r] * C2S + b0 * LOG2E : -1e30f;
	v_sub_u32_e32 v169, v236, v167
	v_cmp_gt_u32_e32 vcc, 16, v169
	v_mul_f32_e32 v111, s21, v111
	v_mul_f32_e32 v168, s20, v95
	v_add_f32_e32 v111, v168, v111
	v_cndmask_b32_e32 v111, v202, v111, vcc

;     ...
;                     s0[r] = ((unsigned)(k0 - csl) < 16u) ? s0[r] * C2S + b0 * LOG2E : -1e30f;
	v_sub_u32_e32 v169, v238, v167
	v_cmp_gt_u32_e32 vcc, 16, v169
	v_mul_f32_e32 v112, s21, v112
	v_mul_f32_e32 v168, s20, v96
	v_add_f32_e32 v112, v168, v112
	v_cndmask_b32_e32 v112, v202, v112, vcc

;     ...
;                     s0[r] = ((unsigned)(k0 - csl) < 16u) ? s0[r] * C2S + b0 * LOG2E : -1e30f;
	v_sub_u32_e32 v169, v240, v167
	v_cmp_gt_u32_e32 vcc, 16, v169
	v_mul_f32_e32 v113, s21, v113
	v_mul_f32_e32 v168, s20, v97
	v_add_f32_e32 v113, v168, v113
	v_cndmask_b32_e32 v113, v202, v113, vcc

; __device__ __forceinline__ int crow(int r, int h) { return (r & 3) + 8 * (r >> 2) + 4 * h; }
;     ...
;                     const int k0 = crow(r, h2), k1 = k0 + 32;
;                     int d0 = k0 - qcl + 15, d1 = k1 - qcl + 15; d0 = d0 < 0 ? 0 : (d0 > 30 ? 30 : d0); d1 = d1 < 0 ? 0 : (d1 > 30 ? 30 : d1);
;                     const float b0 = rpbL[drow + d0], b1 = rpbL[drow + d1];
	v_sub_u32_e32 v82, v188, v114
	v_lshl_add_u32 v82, v82, 2, s4
	v_add_u32_e32 v82, 0xb03c, v82

; __device__ __forceinline__ int crow(int r, int h) { return (r & 3) + 8 * (r >> 2) + 4 * h; }
;     ...
;                     const int k0 = crow(r, h2), k1 = k0 + 32;
;                     int d0 = k0 - qcl + 15, d1 = k1 - qcl + 15; d0 = d0 < 0 ? 0 : (d0 > 30 ? 30 : d0); d1 = d1 < 0 ? 0 : (d1 > 30 ? 30 : d1);
;                     const float b0 = rpbL[drow + d0], b1 = rpbL[drow + d1];
;                     s0[r] = ((unsigned)(k0 - csl) < 16u) ? s0[r] * C2S + b0 * LOG2E : -1e30f;
;                     s1[r] = ((unsigned)(k1 - csl) < 16u) ? s1[r] * C2S + b1 * LOG2E : -1e30f;
;                 }
	ds_read_b32 v115, v82 offset:128
	ds_read_b32 v117, v82 offset:132
	ds_read_b32 v83, v82 offset:136
	ds_read_b32 v119, v82 offset:140
	ds_read_b32 v85, v82 offset:160
	ds_read_b32 v121, v82 offset:164
	ds_read_b32 v87, v82 offset:168
	ds_read_b32 v123, v82 offset:172
	ds_read_b32 v89, v82 offset:192
	ds_read_b32 v125, v82 offset:196
	ds_read_b32 v91, v82 offset:200
	ds_read_b32 v127, v82 offset:204
	ds_read_b32 v93, v82 offset:224
	ds_read_b32 v129, v82 offset:228
	ds_read_b32 v165, v82 offset:232
	ds_read_b32 v95, v82 offset:236
	v_mov_b32_e32 v114, v66
	v_sub_u32_e32 v82, v211, v167
	s_waitcnt lgkmcnt(14)
	v_pk_mul_f32 v[96:97], v[114:115], s[20:21]
	v_mov_b32_e32 v116, v67
	v_cmp_gt_u32_e32 vcc, 16, v82
	v_add_f32_e32 v66, v96, v97
	v_sub_u32_e32 v82, v213, v167
	v_pk_mul_f32 v[96:97], v[116:117], s[20:21]
	v_cndmask_b32_e32 v66, v202, v66, vcc
	v_cmp_gt_u32_e32 vcc, 16, v82
	v_add_f32_e32 v67, v96, v97
	v_sub_u32_e32 v82, v215, v167
	v_cndmask_b32_e32 v67, v202, v67, vcc
	v_cmp_gt_u32_e32 vcc, 16, v82
	v_mov_b32_e32 v82, v68
	s_waitcnt lgkmcnt(13)
	v_pk_mul_f32 v[82:83], v[82:83], s[20:21]
	v_mov_b32_e32 v118, v69
	v_add_f32_e32 v68, v82, v83
	v_sub_u32_e32 v82, v217, v167
	v_cndmask_b32_e32 v68, v202, v68, vcc
	v_cmp_gt_u32_e32 vcc, 16, v82
	s_waitcnt lgkmcnt(12)
	v_pk_mul_f32 v[82:83], v[118:119], s[20:21]
	v_mov_b32_e32 v84, v70
	v_add_f32_e32 v69, v82, v83
	v_sub_u32_e32 v82, v219, v167
	v_cndmask_b32_e32 v69, v202, v69, vcc
	v_cmp_gt_u32_e32 vcc, 16, v82
	s_waitcnt lgkmcnt(11)
	v_pk_mul_f32 v[82:83], v[84:85], s[20:21]
	v_mov_b32_e32 v120, v71
	v_add_f32_e32 v70, v82, v83
	v_sub_u32_e32 v82, v221, v167
	v_cndmask_b32_e32 v70, v202, v70, vcc
	v_cmp_gt_u32_e32 vcc, 16, v82
	s_waitcnt lgkmcnt(10)
	v_pk_mul_f32 v[82:83], v[120:121], s[20:21]
	v_mov_b32_e32 v86, v72
	v_add_f32_e32 v71, v82, v83
	v_sub_u32_e32 v82, v223, v167
	v_cndmask_b32_e32 v71, v202, v71, vcc
	v_cmp_gt_u32_e32 vcc, 16, v82
	s_waitcnt lgkmcnt(9)
	v_pk_mul_f32 v[82:83], v[86:87], s[20:21]
	v_mov_b32_e32 v122, v73
	v_add_f32_e32 v72, v82, v83
	v_sub_u32_e32 v82, v225, v167
	v_cndmask_b32_e32 v72, v202, v72, vcc
	v_cmp_gt_u32_e32 vcc, 16, v82
	s_waitcnt lgkmcnt(8)
	v_pk_mul_f32 v[82:83], v[122:123], s[20:21]
	v_mov_b32_e32 v88, v74
	v_add_f32_e32 v73, v82, v83
	v_sub_u32_e32 v82, v227, v167
	v_cndmask_b32_e32 v73, v202, v73, vcc
	v_cmp_gt_u32_e32 vcc, 16, v82
	s_waitcnt lgkmcnt(7)
	v_pk_mul_f32 v[82:83], v[88:89], s[20:21]
	v_mov_b32_e32 v124, v75
	v_add_f32_e32 v74, v82, v83
	v_sub_u32_e32 v82, v229, v167
	v_cndmask_b32_e32 v74, v202, v74, vcc
	v_cmp_gt_u32_e32 vcc, 16, v82
	s_waitcnt lgkmcnt(6)
	v_pk_mul_f32 v[82:83], v[124:125], s[20:21]
	v_mov_b32_e32 v90, v76
	v_add_f32_e32 v75, v82, v83
	v_sub_u32_e32 v82, v231, v167
	v_cndmask_b32_e32 v75, v202, v75, vcc
	v_cmp_gt_u32_e32 vcc, 16, v82
	s_waitcnt lgkmcnt(5)
	v_pk_mul_f32 v[82:83], v[90:91], s[20:21]
	v_mov_b32_e32 v126, v77
	v_add_f32_e32 v76, v82, v83
	v_sub_u32_e32 v82, v233, v167
	v_cndmask_b32_e32 v76, v202, v76, vcc
	v_cmp_gt_u32_e32 vcc, 16, v82
	s_waitcnt lgkmcnt(4)
	v_pk_mul_f32 v[82:83], v[126:127], s[20:21]
	v_mov_b32_e32 v92, v78
	v_add_f32_e32 v77, v82, v83
	v_sub_u32_e32 v82, v235, v167
	v_cndmask_b32_e32 v77, v202, v77, vcc
	v_cmp_gt_u32_e32 vcc, 16, v82
	s_waitcnt lgkmcnt(3)
	v_pk_mul_f32 v[82:83], v[92:93], s[20:21]
	v_mov_b32_e32 v128, v79
	v_add_f32_e32 v78, v82, v83
	v_sub_u32_e32 v82, v237, v167
	v_cndmask_b32_e32 v78, v202, v78, vcc
	v_cmp_gt_u32_e32 vcc, 16, v82
	s_waitcnt lgkmcnt(2)
	v_pk_mul_f32 v[82:83], v[128:129], s[20:21]
	v_mov_b32_e32 v164, v80
	v_add_f32_e32 v79, v82, v83
	v_sub_u32_e32 v82, v239, v167
	v_cndmask_b32_e32 v79, v202, v79, vcc
	v_cmp_gt_u32_e32 vcc, 16, v82
	s_waitcnt lgkmcnt(1)
	v_pk_mul_f32 v[82:83], v[164:165], s[20:21]
	v_mov_b32_e32 v94, v81
	v_add_f32_e32 v80, v82, v83
	v_sub_u32_e32 v82, v241, v167
	v_cndmask_b32_e32 v80, v202, v80, vcc
	v_cmp_gt_u32_e32 vcc, 16, v82
	s_waitcnt lgkmcnt(0)
	v_pk_mul_f32 v[82:83], v[94:95], s[20:21]
	s_mov_b64 s[48:49], -1
	v_add_f32_e32 v81, v82, v83
	v_mov_b64_e32 v[82:83], v[98:99]
	v_cndmask_b32_e32 v81, v202, v81, vcc
	v_mov_b64_e32 v[84:85], v[100:101]
	v_mov_b64_e32 v[86:87], v[102:103]
	v_mov_b64_e32 v[88:89], v[104:105]
	v_mov_b64_e32 v[90:91], v[106:107]
	v_mov_b64_e32 v[92:93], v[108:109]
	v_mov_b64_e32 v[94:95], v[110:111]
	v_mov_b64_e32 v[96:97], v[112:113]
